# gate epilogue second bias batch prefetched + conv_pass rewrite (4 chunks per trip, weights hoisted) inline
# speedup vs baseline: 1.0372x; 1.0113x over previous
; DI float sigm(float x) { return frcp(1.f + fexp2(-kLog2e * x)); }
; DI unsigned q8fx4(float a, float b, float c, float d) { return q8f(a) | (q8f(b) << 8) | (q8f(c) << 16) | (q8f(d) << 24); }
; DI u32x4* gate_slot(const Params& P, int tile, int j, int g8) { return (u32x4*)slotp(P, SL_SK) + ((size_t)(tile * 3 + j) * 8 + g8) * 512 + tid(); }
; DI void gate_epilogue(const Params& P, int layer, int j, const f32x4 (&acc)[2][2][4][2], int tile, int n0, const char* lds) {
;     LANE_DECODE; (void)lane;
;     const float* rsl = (const float*)(lds + LDS_RS);
; #pragma unroll
;     for (int ai = 0; ai < 2; ++ai) {
;         const int col = n0 + ai * 128 + wr * 64 + 8 * fq;
;         const float* bg = P.b_gate + layer * 3072 + j * 1024 + col;
;         const f32x4 b0 = *(const f32x4*)bg, b1 = *(const f32x4*)(bg + 4), b2 = *(const f32x4*)(bg + 32), b3 = *(const f32x4*)(bg + 36);
; #pragma unroll
;         for (int bj = 0; bj < 2; ++bj)
; #pragma unroll
;             for (int nn = 0; nn < 2; ++nn) {
;                 const int rl = bj * 128 + wc * 32 + nn * 16 + fr;
;                 float lo[8], hi[8];
;                 grp16(acc, ai, bj, nn, rsl[rl], lo, hi);
; #pragma unroll
;                 for (int i = 0; i < 4; ++i) { lo[i] = sigm(lo[i] + b0[i]); lo[4 + i] = sigm(lo[4 + i] + b1[i]); hi[i] = sigm(hi[i] + b2[i]); hi[4 + i] = sigm(hi[4 + i] + b3[i]); }
;                 u32x4 o = {q8fx4(lo[0], lo[1], lo[2], lo[3]), q8fx4(lo[4], lo[5], lo[6], lo[7]), q8fx4(hi[0], hi[1], hi[2], hi[3]), q8fx4(hi[4], hi[5], hi[6], hi[7])};
;                 *gate_slot(P, tile, j, ai * 4 + bj * 2 + nn) = o;
;                 __builtin_amdgcn_sched_barrier(0);
;             }
;     }
; }
.LBB0_46:
	s_or_b64 exec, exec, s[22:23]
	v_mov_b32_e32 v0, v162
	s_waitcnt vmcnt(0)
	s_barrier
	s_add_i32 s22, s3, s58
	v_ashrrev_i32_e32 v82, 2, v0
	v_and_b32_e32 v82, 0xffffffc0, v82
	s_ashr_i32 s23, s22, 31
	v_lshrrev_b32_e32 v83, 1, v0
	v_add_u32_e32 v82, s14, v82
	s_lshl_b64 s[22:23], s[22:23], 16
	s_lshl_b64 s[24:25], s[82:83], 2
	v_and_or_b32 v82, v83, 24, v82
	s_add_u32 s24, s64, s24
	s_addc_u32 s25, s27, s25
	v_ashrrev_i32_e32 v83, 31, v82
	v_lshl_add_u64 v[146:147], v[82:83], 2, s[24:25]
	global_load_dwordx4 v[94:97], v[146:147], off
	global_load_dwordx4 v[90:93], v[146:147], off offset:16
	global_load_dwordx4 v[86:89], v[146:147], off offset:128
	global_load_dwordx4 v[82:85], v[146:147], off offset:144
	global_load_dwordx4 v[200:203], v[146:147], off offset:512
	global_load_dwordx4 v[204:207], v[146:147], off offset:528
	global_load_dwordx4 v[208:211], v[146:147], off offset:640
	global_load_dwordx4 v[212:215], v[146:147], off offset:656
	v_and_b32_e32 v148, 15, v0
	v_lshlrev_b32_e32 v0, 1, v0
	v_lshlrev_b32_e32 v148, 2, v148
	s_movk_i32 s7, 0x180
	v_and_or_b32 v149, v0, s7, v148
	v_or_b32_e32 v148, 0x20000, v149
	ds_read_b32 v0, v148
	s_add_u32 s24, s74, s22
	s_addc_u32 s25, s75, s23
	s_waitcnt vmcnt(7) lgkmcnt(0)
	v_fma_f32 v142, v142, v0, v94
	v_fma_f32 v143, v143, v0, v95
	v_fma_f32 v144, v144, v0, v96
	s_waitcnt vmcnt(4)
	v_fma_f32 v130, v130, v0, v82
	v_fma_f32 v131, v131, v0, v83
	v_fma_f32 v132, v132, v0, v84
	v_fma_f32 v145, v145, v0, v97
	v_mul_f32_e32 v142, 0xbfb8aa3b, v142
	v_mul_f32_e32 v130, 0xbfb8aa3b, v130
	v_mul_f32_e32 v143, 0xbfb8aa3b, v143
	v_mul_f32_e32 v131, 0xbfb8aa3b, v131
	v_mul_f32_e32 v144, 0xbfb8aa3b, v144
	v_mul_f32_e32 v132, 0xbfb8aa3b, v132
	v_mul_f32_e32 v145, 0xbfb8aa3b, v145
	v_exp_f32_e32 v142, v142
	v_exp_f32_e32 v130, v130
	v_exp_f32_e32 v143, v143
	v_exp_f32_e32 v131, v131
	v_exp_f32_e32 v144, v144
	v_exp_f32_e32 v132, v132
	v_exp_f32_e32 v145, v145
	v_add_f32_e32 v142, 1.0, v142
	v_add_f32_e32 v130, 1.0, v130
	v_add_f32_e32 v143, 1.0, v143
	v_fma_f32 v138, v138, v0, v90
	v_fma_f32 v139, v139, v0, v91
	v_fma_f32 v137, v137, v0, v89
	v_add_f32_e32 v131, 1.0, v131
	v_add_f32_e32 v144, 1.0, v144
	v_add_f32_e32 v132, 1.0, v132
	v_add_f32_e32 v145, 1.0, v145
	v_rcp_f32_e32 v142, v142
	v_rcp_f32_e32 v150, v130
	v_rcp_f32_e32 v130, v143
	v_fma_f32 v140, v140, v0, v92
	v_mul_f32_e32 v138, 0xbfb8aa3b, v138
	v_mul_f32_e32 v139, 0xbfb8aa3b, v139
	v_rcp_f32_e32 v143, v131
	v_rcp_f32_e32 v131, v144
	v_rcp_f32_e32 v144, v132
	v_mul_f32_e32 v132, 0xbfb8aa3b, v137
	v_rcp_f32_e32 v137, v145
	v_mul_f32_e32 v140, 0xbfb8aa3b, v140
	v_exp_f32_e32 v138, v138
	v_exp_f32_e32 v139, v139
	v_exp_f32_e32 v140, v140
	v_fma_f32 v134, v134, v0, v86
	v_fma_f32 v135, v135, v0, v87
	v_fma_f32 v136, v136, v0, v88
	v_fma_f32 v141, v141, v0, v93
	v_fma_f32 v0, v133, v0, v85
	v_fma_f32 v133, v142, s80, 0.5
	v_fma_f32 v130, v130, s80, 0.5
	v_cvt_u32_f32_e32 v133, v133
	v_cvt_u32_f32_e32 v130, v130
	v_fma_f32 v131, v131, s80, 0.5
	v_fma_f32 v137, v137, s80, 0.5
	v_add_f32_e32 v138, 1.0, v138
	v_add_f32_e32 v139, 1.0, v139
	v_cvt_u32_f32_e32 v131, v131
	v_cvt_u32_f32_e32 v137, v137
	v_mul_f32_e32 v141, 0xbfb8aa3b, v141
	v_add_f32_e32 v140, 1.0, v140
	v_rcp_f32_e32 v138, v138
	v_rcp_f32_e32 v139, v139
	v_mul_f32_e32 v134, 0xbfb8aa3b, v134
	v_mul_f32_e32 v135, 0xbfb8aa3b, v135
	v_exp_f32_e32 v141, v141
	v_rcp_f32_e32 v140, v140
	v_exp_f32_e32 v134, v134
	v_exp_f32_e32 v135, v135
	v_max_u32_e32 v133, 1, v133
	v_max_u32_e32 v130, 1, v130
	v_lshl_or_b32 v130, v130, 8, v133
	v_max_u32_sdwa v131, v131, v175 dst_sel:WORD_1 dst_unused:UNUSED_PAD src0_sel:DWORD src1_sel:DWORD
	v_max_u32_sdwa v133, v137, v175 dst_sel:BYTE_3 dst_unused:UNUSED_PAD src0_sel:DWORD src1_sel:DWORD
	v_add_f32_e32 v141, 1.0, v141
	v_or3_b32 v130, v130, v131, v133
	v_fma_f32 v131, v138, s80, 0.5
	v_fma_f32 v133, v139, s80, 0.5
	v_cvt_u32_f32_e32 v131, v131
	v_cvt_u32_f32_e32 v133, v133
	v_fma_f32 v137, v140, s80, 0.5
	v_add_f32_e32 v134, 1.0, v134
	v_add_f32_e32 v135, 1.0, v135
	v_rcp_f32_e32 v141, v141
	v_cvt_u32_f32_e32 v137, v137
	v_mul_f32_e32 v136, 0xbfb8aa3b, v136
	v_rcp_f32_e32 v134, v134
	v_rcp_f32_e32 v135, v135
	v_exp_f32_e32 v136, v136
	v_exp_f32_e32 v132, v132
	v_max_u32_e32 v131, 1, v131
	v_max_u32_e32 v133, 1, v133
	v_lshl_or_b32 v131, v133, 8, v131
	v_max_u32_sdwa v133, v137, v175 dst_sel:WORD_1 dst_unused:UNUSED_PAD src0_sel:DWORD src1_sel:DWORD
	v_fma_f32 v137, v141, s80, 0.5
	v_cvt_u32_f32_e32 v137, v137
	v_fma_f32 v134, v134, s80, 0.5
	v_fma_f32 v135, v135, s80, 0.5
	v_add_f32_e32 v136, 1.0, v136
	v_add_f32_e32 v132, 1.0, v132
	v_cvt_u32_f32_e32 v134, v134
	v_cvt_u32_f32_e32 v135, v135
	v_rcp_f32_e32 v136, v136
	v_rcp_f32_e32 v132, v132
	v_mul_f32_e32 v0, 0xbfb8aa3b, v0
	v_exp_f32_e32 v0, v0
	v_max_u32_sdwa v137, v137, v175 dst_sel:BYTE_3 dst_unused:UNUSED_PAD src0_sel:DWORD src1_sel:DWORD
	v_fma_f32 v132, v132, s80, 0.5
	v_or3_b32 v131, v131, v133, v137
	v_max_u32_e32 v133, 1, v134
	v_max_u32_e32 v134, 1, v135
	v_lshl_or_b32 v133, v134, 8, v133
	v_fma_f32 v134, v136, s80, 0.5
	v_cvt_u32_f32_e32 v134, v134
	v_cvt_u32_f32_e32 v132, v132
	v_add_f32_e32 v0, 1.0, v0
	v_fma_f32 v135, v150, s80, 0.5
	v_rcp_f32_e32 v0, v0
	v_cvt_u32_f32_e32 v135, v135
	v_max_u32_sdwa v134, v134, v175 dst_sel:WORD_1 dst_unused:UNUSED_PAD src0_sel:DWORD src1_sel:DWORD
	v_max_u32_sdwa v132, v132, v175 dst_sel:BYTE_3 dst_unused:UNUSED_PAD src0_sel:DWORD src1_sel:DWORD
	v_fma_f32 v0, v0, s80, 0.5
	v_or3_b32 v132, v133, v134, v132
	v_fma_f32 v134, v143, s80, 0.5
	v_max_u32_e32 v133, 1, v135
	v_cvt_u32_f32_e32 v134, v134
	v_fma_f32 v135, v144, s80, 0.5
	v_cvt_u32_f32_e32 v135, v135
	v_cvt_u32_f32_e32 v0, v0
	v_max_u32_e32 v134, 1, v134
	v_lshl_or_b32 v133, v134, 8, v133
	v_max_u32_sdwa v134, v135, v175 dst_sel:WORD_1 dst_unused:UNUSED_PAD src0_sel:DWORD src1_sel:DWORD
	v_max_u32_sdwa v0, v0, v175 dst_sel:BYTE_3 dst_unused:UNUSED_PAD src0_sel:DWORD src1_sel:DWORD
	s_nop 0
	v_or3_b32 v133, v133, v134, v0
	v_mov_b32_e32 v134, v162
	s_nop 0
	v_ashrrev_i32_e32 v135, 31, v134
	v_lshl_add_u64 v[134:135], v[134:135], 4, s[24:25]
	global_store_dwordx4 v[134:135], v[130:133], off
	v_or_b32_e32 v0, 0x20040, v149
	ds_read_b32 v130, v0
	s_add_u32 s22, s62, s22
	s_addc_u32 s23, s63, s23
	s_mov_b32 s7, 0x13802000
	s_waitcnt lgkmcnt(0)
; DI float sigm(float x) { return frcp(1.f + fexp2(-kLog2e * x)); }
; DI unsigned q8fx4(float a, float b, float c, float d) { return q8f(a) | (q8f(b) << 8) | (q8f(c) << 16) | (q8f(d) << 24); }
; DI u32x4* gate_slot(const Params& P, int tile, int j, int g8) { return (u32x4*)slotp(P, SL_SK) + ((size_t)(tile * 3 + j) * 8 + g8) * 512 + tid(); }
; DI void gate_epilogue(const Params& P, int layer, int j, const f32x4 (&acc)[2][2][4][2], int tile, int n0, const char* lds) {
;     ...
;                 const int rl = bj * 128 + wc * 32 + nn * 16 + fr;
;                 float lo[8], hi[8];
;                 grp16(acc, ai, bj, nn, rsl[rl], lo, hi);
; #pragma unroll
;                 for (int i = 0; i < 4; ++i) { lo[i] = sigm(lo[i] + b0[i]); lo[4 + i] = sigm(lo[4 + i] + b1[i]); hi[i] = sigm(hi[i] + b2[i]); hi[4 + i] = sigm(hi[4 + i] + b3[i]); }
;                 u32x4 o = {q8fx4(lo[0], lo[1], lo[2], lo[3]), q8fx4(lo[4], lo[5], lo[6], lo[7]), q8fx4(hi[0], hi[1], hi[2], hi[3]), q8fx4(hi[4], hi[5], hi[6], hi[7])};
;                 *gate_slot(P, tile, j, ai * 4 + bj * 2 + nn) = o;
	v_fma_f32 v114, v114, v130, v82
	v_mul_f32_e32 v114, 0xbfb8aa3b, v114
	v_fma_f32 v127, v127, v130, v95
	v_exp_f32_e32 v114, v114
	v_mul_f32_e32 v127, 0xbfb8aa3b, v127
	v_exp_f32_e32 v127, v127
	v_fma_f32 v115, v115, v130, v83
	v_add_f32_e32 v114, 1.0, v114
	v_rcp_f32_e32 v131, v114
	v_add_f32_e32 v114, 1.0, v127
	v_mul_f32_e32 v115, 0xbfb8aa3b, v115
	v_fma_f32 v127, v128, v130, v96
	v_exp_f32_e32 v115, v115
	v_mul_f32_e32 v127, 0xbfb8aa3b, v127
	v_exp_f32_e32 v127, v127
	v_fma_f32 v126, v126, v130, v94
	v_add_f32_e32 v115, 1.0, v115
	v_fma_f32 v116, v116, v130, v84
	v_mul_f32_e32 v126, 0xbfb8aa3b, v126
	v_rcp_f32_e32 v128, v115
	v_add_f32_e32 v115, 1.0, v127
	v_mul_f32_e32 v116, 0xbfb8aa3b, v116
	v_fma_f32 v127, v129, v130, v97
	v_exp_f32_e32 v126, v126
	v_exp_f32_e32 v116, v116
	v_mul_f32_e32 v127, 0xbfb8aa3b, v127
	v_exp_f32_e32 v127, v127
	v_add_f32_e32 v126, 1.0, v126
	v_add_f32_e32 v116, 1.0, v116
	v_fma_f32 v122, v122, v130, v90
	v_rcp_f32_e32 v126, v126
	v_fma_f32 v123, v123, v130, v91
	v_rcp_f32_e32 v114, v114
	v_rcp_f32_e32 v129, v116
	v_add_f32_e32 v116, 1.0, v127
	v_mul_f32_e32 v122, 0xbfb8aa3b, v122
	v_mul_f32_e32 v123, 0xbfb8aa3b, v123
	v_fma_f32 v124, v124, v130, v92
	v_rcp_f32_e32 v115, v115
	v_rcp_f32_e32 v116, v116
	v_exp_f32_e32 v122, v122
	v_exp_f32_e32 v123, v123
	v_mul_f32_e32 v124, 0xbfb8aa3b, v124
	v_exp_f32_e32 v124, v124
	v_fma_f32 v126, v126, s80, 0.5
	v_fma_f32 v114, v114, s80, 0.5
	v_cvt_u32_f32_e32 v126, v126
	v_cvt_u32_f32_e32 v114, v114
	v_fma_f32 v115, v115, s80, 0.5
	v_fma_f32 v116, v116, s80, 0.5
	v_add_f32_e32 v122, 1.0, v122
	v_add_f32_e32 v123, 1.0, v123
	v_fma_f32 v125, v125, v130, v93
	v_cvt_u32_f32_e32 v115, v115
	v_cvt_u32_f32_e32 v116, v116
	v_fma_f32 v118, v118, v130, v86
	v_rcp_f32_e32 v122, v122
	v_fma_f32 v119, v119, v130, v87
	v_rcp_f32_e32 v123, v123
	v_add_f32_e32 v124, 1.0, v124
	v_mul_f32_e32 v125, 0xbfb8aa3b, v125
	v_mul_f32_e32 v118, 0xbfb8aa3b, v118
	v_mul_f32_e32 v119, 0xbfb8aa3b, v119
	v_rcp_f32_e32 v124, v124
	v_exp_f32_e32 v125, v125
	v_exp_f32_e32 v118, v118
	v_exp_f32_e32 v119, v119
	v_max_u32_e32 v126, 1, v126
	v_max_u32_e32 v114, 1, v114
	v_lshl_or_b32 v114, v114, 8, v126
	v_max_u32_sdwa v115, v115, v175 dst_sel:WORD_1 dst_unused:UNUSED_PAD src0_sel:DWORD src1_sel:DWORD
	v_max_u32_sdwa v116, v116, v175 dst_sel:BYTE_3 dst_unused:UNUSED_PAD src0_sel:DWORD src1_sel:DWORD
	v_add_f32_e32 v125, 1.0, v125
	v_or3_b32 v114, v114, v115, v116
	v_fma_f32 v115, v122, s80, 0.5
	v_fma_f32 v116, v123, s80, 0.5
	v_cvt_u32_f32_e32 v115, v115
	v_cvt_u32_f32_e32 v116, v116
	v_fma_f32 v122, v124, s80, 0.5
	v_add_f32_e32 v118, 1.0, v118
	v_add_f32_e32 v119, 1.0, v119
	v_fma_f32 v120, v120, v130, v88
	v_fma_f32 v121, v121, v130, v89
	v_rcp_f32_e32 v125, v125
	v_cvt_u32_f32_e32 v122, v122
	v_rcp_f32_e32 v118, v118
	v_rcp_f32_e32 v119, v119
	v_mul_f32_e32 v120, 0xbfb8aa3b, v120
	v_mul_f32_e32 v121, 0xbfb8aa3b, v121
	v_exp_f32_e32 v120, v120
	v_exp_f32_e32 v121, v121
	v_max_u32_e32 v115, 1, v115
	v_max_u32_e32 v116, 1, v116
	v_lshl_or_b32 v115, v116, 8, v115
	v_max_u32_sdwa v116, v122, v175 dst_sel:WORD_1 dst_unused:UNUSED_PAD src0_sel:DWORD src1_sel:DWORD
	v_fma_f32 v122, v125, s80, 0.5
	v_cvt_u32_f32_e32 v122, v122
	v_fma_f32 v118, v118, s80, 0.5
	v_fma_f32 v119, v119, s80, 0.5
	v_add_f32_e32 v120, 1.0, v120
	v_add_f32_e32 v121, 1.0, v121
	v_cvt_u32_f32_e32 v118, v118
	v_cvt_u32_f32_e32 v119, v119
	v_rcp_f32_e32 v120, v120
	v_fma_f32 v117, v117, v130, v85
	v_rcp_f32_e32 v121, v121
	v_mul_f32_e32 v117, 0xbfb8aa3b, v117
	v_exp_f32_e32 v117, v117
	v_max_u32_sdwa v122, v122, v175 dst_sel:BYTE_3 dst_unused:UNUSED_PAD src0_sel:DWORD src1_sel:DWORD
	v_add_f32_e32 v117, 1.0, v117
	v_or3_b32 v115, v115, v116, v122
	v_max_u32_e32 v116, 1, v118
	v_max_u32_e32 v118, 1, v119
	v_lshl_or_b32 v116, v118, 8, v116
	v_fma_f32 v118, v120, s80, 0.5
	v_fma_f32 v119, v121, s80, 0.5
	v_cvt_u32_f32_e32 v118, v118
	v_cvt_u32_f32_e32 v119, v119
	v_fma_f32 v120, v131, s80, 0.5
	v_rcp_f32_e32 v117, v117
	v_cvt_u32_f32_e32 v120, v120
	v_max_u32_sdwa v118, v118, v175 dst_sel:WORD_1 dst_unused:UNUSED_PAD src0_sel:DWORD src1_sel:DWORD
	v_max_u32_sdwa v119, v119, v175 dst_sel:BYTE_3 dst_unused:UNUSED_PAD src0_sel:DWORD src1_sel:DWORD
	v_fma_f32 v117, v117, s80, 0.5
	v_or3_b32 v116, v116, v118, v119
	v_fma_f32 v119, v128, s80, 0.5
	v_max_u32_e32 v118, 1, v120
	v_cvt_u32_f32_e32 v119, v119
	v_fma_f32 v120, v129, s80, 0.5
	v_cvt_u32_f32_e32 v120, v120
	v_cvt_u32_f32_e32 v117, v117
	v_max_u32_e32 v119, 1, v119
	v_lshl_or_b32 v118, v119, 8, v118
	v_max_u32_sdwa v119, v120, v175 dst_sel:WORD_1 dst_unused:UNUSED_PAD src0_sel:DWORD src1_sel:DWORD
	v_max_u32_sdwa v117, v117, v175 dst_sel:BYTE_3 dst_unused:UNUSED_PAD src0_sel:DWORD src1_sel:DWORD
	s_nop 0
	v_or3_b32 v117, v118, v119, v117
	v_mov_b32_e32 v118, v162
	s_nop 0
	v_ashrrev_i32_e32 v119, 31, v118
	v_lshl_add_u64 v[118:119], v[118:119], 4, s[22:23]
	v_add_co_u32_e32 v118, vcc, s7, v118
	s_nop 1
	v_addc_co_u32_e32 v119, vcc, 0, v119, vcc
	global_store_dwordx4 v[118:119], v[114:117], off
	s_nop 1
	v_or_b32_e32 v114, 0x20200, v149
	ds_read_b32 v115, v114
	s_mov_b32 s7, 0x13804000
	s_waitcnt lgkmcnt(0)
; DI float sigm(float x) { return frcp(1.f + fexp2(-kLog2e * x)); }
; DI unsigned q8fx4(float a, float b, float c, float d) { return q8f(a) | (q8f(b) << 8) | (q8f(c) << 16) | (q8f(d) << 24); }
; DI u32x4* gate_slot(const Params& P, int tile, int j, int g8) { return (u32x4*)slotp(P, SL_SK) + ((size_t)(tile * 3 + j) * 8 + g8) * 512 + tid(); }
; DI void gate_epilogue(const Params& P, int layer, int j, const f32x4 (&acc)[2][2][4][2], int tile, int n0, const char* lds) {
;     ...
;                 const int rl = bj * 128 + wc * 32 + nn * 16 + fr;
;                 float lo[8], hi[8];
;                 grp16(acc, ai, bj, nn, rsl[rl], lo, hi);
; #pragma unroll
;                 for (int i = 0; i < 4; ++i) { lo[i] = sigm(lo[i] + b0[i]); lo[4 + i] = sigm(lo[4 + i] + b1[i]); hi[i] = sigm(hi[i] + b2[i]); hi[4 + i] = sigm(hi[4 + i] + b3[i]); }
;                 u32x4 o = {q8fx4(lo[0], lo[1], lo[2], lo[3]), q8fx4(lo[4], lo[5], lo[6], lo[7]), q8fx4(hi[0], hi[1], hi[2], hi[3]), q8fx4(hi[4], hi[5], hi[6], hi[7])};
;                 *gate_slot(P, tile, j, ai * 4 + bj * 2 + nn) = o;
	v_fma_f32 v98, v98, v115, v82
	v_mul_f32_e32 v98, 0xbfb8aa3b, v98
	v_fma_f32 v111, v111, v115, v95
	v_exp_f32_e32 v98, v98
	v_mul_f32_e32 v111, 0xbfb8aa3b, v111
	v_exp_f32_e32 v111, v111
	v_fma_f32 v99, v99, v115, v83
	v_add_f32_e32 v98, 1.0, v98
	v_rcp_f32_e32 v116, v98
	v_add_f32_e32 v98, 1.0, v111
	v_mul_f32_e32 v99, 0xbfb8aa3b, v99
	v_fma_f32 v111, v112, v115, v96
	v_exp_f32_e32 v99, v99
	v_mul_f32_e32 v111, 0xbfb8aa3b, v111
	v_exp_f32_e32 v111, v111
	v_fma_f32 v110, v110, v115, v94
	v_add_f32_e32 v99, 1.0, v99
	v_fma_f32 v100, v100, v115, v84
	v_mul_f32_e32 v110, 0xbfb8aa3b, v110
	v_rcp_f32_e32 v112, v99
	v_add_f32_e32 v99, 1.0, v111
	v_mul_f32_e32 v100, 0xbfb8aa3b, v100
	v_fma_f32 v111, v113, v115, v97
	v_exp_f32_e32 v110, v110
	v_exp_f32_e32 v100, v100
	v_mul_f32_e32 v111, 0xbfb8aa3b, v111
	v_exp_f32_e32 v111, v111
	v_add_f32_e32 v110, 1.0, v110
	v_add_f32_e32 v100, 1.0, v100
	v_fma_f32 v106, v106, v115, v90
	v_rcp_f32_e32 v110, v110
	v_fma_f32 v107, v107, v115, v91
	v_rcp_f32_e32 v98, v98
	v_rcp_f32_e32 v113, v100
	v_add_f32_e32 v100, 1.0, v111
	v_mul_f32_e32 v106, 0xbfb8aa3b, v106
	v_mul_f32_e32 v107, 0xbfb8aa3b, v107
	v_fma_f32 v108, v108, v115, v92
	v_rcp_f32_e32 v99, v99
	v_rcp_f32_e32 v100, v100
	v_exp_f32_e32 v106, v106
	v_exp_f32_e32 v107, v107
	v_mul_f32_e32 v108, 0xbfb8aa3b, v108
	v_exp_f32_e32 v108, v108
	v_fma_f32 v110, v110, s80, 0.5
	v_fma_f32 v98, v98, s80, 0.5
	v_cvt_u32_f32_e32 v110, v110
	v_cvt_u32_f32_e32 v98, v98
	v_fma_f32 v99, v99, s80, 0.5
	v_fma_f32 v100, v100, s80, 0.5
	v_add_f32_e32 v106, 1.0, v106
	v_add_f32_e32 v107, 1.0, v107
	v_fma_f32 v109, v109, v115, v93
	v_cvt_u32_f32_e32 v99, v99
	v_cvt_u32_f32_e32 v100, v100
	v_fma_f32 v102, v102, v115, v86
	v_rcp_f32_e32 v106, v106
	v_fma_f32 v103, v103, v115, v87
	v_rcp_f32_e32 v107, v107
	v_add_f32_e32 v108, 1.0, v108
	v_mul_f32_e32 v109, 0xbfb8aa3b, v109
	v_mul_f32_e32 v102, 0xbfb8aa3b, v102
	v_mul_f32_e32 v103, 0xbfb8aa3b, v103
	v_rcp_f32_e32 v108, v108
	v_exp_f32_e32 v109, v109
	v_exp_f32_e32 v102, v102
	v_exp_f32_e32 v103, v103
	v_max_u32_e32 v110, 1, v110
	v_max_u32_e32 v98, 1, v98
	v_lshl_or_b32 v98, v98, 8, v110
	v_max_u32_sdwa v99, v99, v175 dst_sel:WORD_1 dst_unused:UNUSED_PAD src0_sel:DWORD src1_sel:DWORD
	v_max_u32_sdwa v100, v100, v175 dst_sel:BYTE_3 dst_unused:UNUSED_PAD src0_sel:DWORD src1_sel:DWORD
	v_add_f32_e32 v109, 1.0, v109
	v_or3_b32 v98, v98, v99, v100
	v_fma_f32 v99, v106, s80, 0.5
	v_fma_f32 v100, v107, s80, 0.5
	v_cvt_u32_f32_e32 v99, v99
	v_cvt_u32_f32_e32 v100, v100
	v_fma_f32 v106, v108, s80, 0.5
	v_add_f32_e32 v102, 1.0, v102
	v_add_f32_e32 v103, 1.0, v103
	v_fma_f32 v104, v104, v115, v88
	v_fma_f32 v105, v105, v115, v89
	v_rcp_f32_e32 v109, v109
	v_cvt_u32_f32_e32 v106, v106
	v_rcp_f32_e32 v102, v102
	v_rcp_f32_e32 v103, v103
	v_mul_f32_e32 v104, 0xbfb8aa3b, v104
	v_mul_f32_e32 v105, 0xbfb8aa3b, v105
	v_exp_f32_e32 v104, v104
	v_exp_f32_e32 v105, v105
	v_max_u32_e32 v99, 1, v99
	v_max_u32_e32 v100, 1, v100
	v_lshl_or_b32 v99, v100, 8, v99
	v_max_u32_sdwa v100, v106, v175 dst_sel:WORD_1 dst_unused:UNUSED_PAD src0_sel:DWORD src1_sel:DWORD
	v_fma_f32 v106, v109, s80, 0.5
	v_cvt_u32_f32_e32 v106, v106
	v_fma_f32 v102, v102, s80, 0.5
	v_fma_f32 v103, v103, s80, 0.5
	v_add_f32_e32 v104, 1.0, v104
	v_add_f32_e32 v105, 1.0, v105
	v_cvt_u32_f32_e32 v102, v102
	v_cvt_u32_f32_e32 v103, v103
	v_rcp_f32_e32 v104, v104
	v_fma_f32 v101, v101, v115, v85
	v_rcp_f32_e32 v105, v105
	v_mul_f32_e32 v101, 0xbfb8aa3b, v101
	v_exp_f32_e32 v101, v101
	v_max_u32_sdwa v106, v106, v175 dst_sel:BYTE_3 dst_unused:UNUSED_PAD src0_sel:DWORD src1_sel:DWORD
	v_add_f32_e32 v101, 1.0, v101
	v_or3_b32 v99, v99, v100, v106
	v_max_u32_e32 v100, 1, v102
	v_max_u32_e32 v102, 1, v103
	v_lshl_or_b32 v100, v102, 8, v100
	v_fma_f32 v102, v104, s80, 0.5
	v_fma_f32 v103, v105, s80, 0.5
	v_cvt_u32_f32_e32 v102, v102
	v_cvt_u32_f32_e32 v103, v103
	v_fma_f32 v104, v116, s80, 0.5
	v_rcp_f32_e32 v101, v101
	v_cvt_u32_f32_e32 v104, v104
	v_max_u32_sdwa v102, v102, v175 dst_sel:WORD_1 dst_unused:UNUSED_PAD src0_sel:DWORD src1_sel:DWORD
	v_max_u32_sdwa v103, v103, v175 dst_sel:BYTE_3 dst_unused:UNUSED_PAD src0_sel:DWORD src1_sel:DWORD
	v_fma_f32 v101, v101, s80, 0.5
	v_or3_b32 v100, v100, v102, v103
	v_fma_f32 v103, v112, s80, 0.5
	v_max_u32_e32 v102, 1, v104
	v_cvt_u32_f32_e32 v103, v103
	v_fma_f32 v104, v113, s80, 0.5
	v_cvt_u32_f32_e32 v104, v104
	v_cvt_u32_f32_e32 v101, v101
	v_max_u32_e32 v103, 1, v103
	v_lshl_or_b32 v102, v103, 8, v102
	v_max_u32_sdwa v103, v104, v175 dst_sel:WORD_1 dst_unused:UNUSED_PAD src0_sel:DWORD src1_sel:DWORD
	v_max_u32_sdwa v101, v101, v175 dst_sel:BYTE_3 dst_unused:UNUSED_PAD src0_sel:DWORD src1_sel:DWORD
	s_nop 0
	v_or3_b32 v101, v102, v103, v101
	v_mov_b32_e32 v102, v162
	s_nop 0
	v_ashrrev_i32_e32 v103, 31, v102
	v_lshl_add_u64 v[102:103], v[102:103], 4, s[22:23]
	v_add_co_u32_e32 v102, vcc, s7, v102
	s_nop 1
	v_addc_co_u32_e32 v103, vcc, 0, v103, vcc
	global_store_dwordx4 v[102:103], v[98:101], off
	s_nop 1
	v_or_b32_e32 v98, 0x20240, v149
	ds_read_b32 v99, v98
	s_mov_b32 s7, 0x13806000
	s_waitcnt lgkmcnt(0)
; DI float sigm(float x) { return frcp(1.f + fexp2(-kLog2e * x)); }
; DI unsigned q8fx4(float a, float b, float c, float d) { return q8f(a) | (q8f(b) << 8) | (q8f(c) << 16) | (q8f(d) << 24); }
; DI u32x4* gate_slot(const Params& P, int tile, int j, int g8) { return (u32x4*)slotp(P, SL_SK) + ((size_t)(tile * 3 + j) * 8 + g8) * 512 + tid(); }
; DI void gate_epilogue(const Params& P, int layer, int j, const f32x4 (&acc)[2][2][4][2], int tile, int n0, const char* lds) {
;     ...
;         const int col = n0 + ai * 128 + wr * 64 + 8 * fq;
;         const float* bg = P.b_gate + layer * 3072 + j * 1024 + col;
;         const f32x4 b0 = *(const f32x4*)bg, b1 = *(const f32x4*)(bg + 4), b2 = *(const f32x4*)(bg + 32), b3 = *(const f32x4*)(bg + 36);
; #pragma unroll
;         for (int bj = 0; bj < 2; ++bj)
; #pragma unroll
;             for (int nn = 0; nn < 2; ++nn) {
;                 const int rl = bj * 128 + wc * 32 + nn * 16 + fr;
;                 float lo[8], hi[8];
;                 grp16(acc, ai, bj, nn, rsl[rl], lo, hi);
; #pragma unroll
;                 for (int i = 0; i < 4; ++i) { lo[i] = sigm(lo[i] + b0[i]); lo[4 + i] = sigm(lo[4 + i] + b1[i]); hi[i] = sigm(hi[i] + b2[i]); hi[4 + i] = sigm(hi[4 + i] + b3[i]); }
;                 u32x4 o = {q8fx4(lo[0], lo[1], lo[2], lo[3]), q8fx4(lo[4], lo[5], lo[6], lo[7]), q8fx4(hi[0], hi[1], hi[2], hi[3]), q8fx4(hi[4], hi[5], hi[6], hi[7])};
;                 *gate_slot(P, tile, j, ai * 4 + bj * 2 + nn) = o;
	v_fma_f32 v66, v66, v99, v82
	v_mul_f32_e32 v66, 0xbfb8aa3b, v66
	v_fma_f32 v79, v79, v99, v95
	v_exp_f32_e32 v66, v66
	v_mul_f32_e32 v79, 0xbfb8aa3b, v79
	v_exp_f32_e32 v79, v79
	v_fma_f32 v67, v67, v99, v83
	v_add_f32_e32 v66, 1.0, v66
	v_rcp_f32_e32 v82, v66
	v_add_f32_e32 v66, 1.0, v79
	v_mul_f32_e32 v67, 0xbfb8aa3b, v67
	v_fma_f32 v79, v80, v99, v96
	v_exp_f32_e32 v67, v67
	v_mul_f32_e32 v79, 0xbfb8aa3b, v79
	v_exp_f32_e32 v79, v79
	v_fma_f32 v78, v78, v99, v94
	v_fma_f32 v68, v68, v99, v84
	v_mul_f32_e32 v78, 0xbfb8aa3b, v78
	v_add_f32_e32 v67, 1.0, v67
	v_mul_f32_e32 v68, 0xbfb8aa3b, v68
	v_fmac_f32_e32 v97, v81, v99
	v_exp_f32_e32 v78, v78
	v_rcp_f32_e32 v80, v67
	v_add_f32_e32 v67, 1.0, v79
	v_exp_f32_e32 v68, v68
	v_mul_f32_e32 v79, 0xbfb8aa3b, v97
	v_exp_f32_e32 v79, v79
	v_add_f32_e32 v78, 1.0, v78
	v_add_f32_e32 v68, 1.0, v68
	v_fma_f32 v74, v74, v99, v90
	v_rcp_f32_e32 v78, v78
	v_fma_f32 v75, v75, v99, v91
	v_rcp_f32_e32 v66, v66
	v_rcp_f32_e32 v81, v68
	v_add_f32_e32 v68, 1.0, v79
	v_mul_f32_e32 v74, 0xbfb8aa3b, v74
	v_mul_f32_e32 v75, 0xbfb8aa3b, v75
	v_fma_f32 v76, v76, v99, v92
	v_rcp_f32_e32 v67, v67
	v_rcp_f32_e32 v68, v68
	v_exp_f32_e32 v74, v74
	v_exp_f32_e32 v75, v75
	v_mul_f32_e32 v76, 0xbfb8aa3b, v76
	v_exp_f32_e32 v76, v76
	v_fma_f32 v78, v78, s80, 0.5
	v_fma_f32 v66, v66, s80, 0.5
	v_cvt_u32_f32_e32 v78, v78
	v_cvt_u32_f32_e32 v66, v66
	v_fma_f32 v67, v67, s80, 0.5
	v_fma_f32 v68, v68, s80, 0.5
	v_add_f32_e32 v74, 1.0, v74
	v_add_f32_e32 v75, 1.0, v75
	v_fmac_f32_e32 v93, v77, v99
	v_cvt_u32_f32_e32 v67, v67
	v_cvt_u32_f32_e32 v68, v68
	v_fma_f32 v70, v70, v99, v86
	v_rcp_f32_e32 v74, v74
	v_fma_f32 v71, v71, v99, v87
	v_rcp_f32_e32 v75, v75
	v_add_f32_e32 v76, 1.0, v76
	v_mul_f32_e32 v77, 0xbfb8aa3b, v93
	v_mul_f32_e32 v70, 0xbfb8aa3b, v70
	v_mul_f32_e32 v71, 0xbfb8aa3b, v71
	v_rcp_f32_e32 v76, v76
	v_exp_f32_e32 v77, v77
	v_exp_f32_e32 v70, v70
	v_exp_f32_e32 v71, v71
	v_max_u32_e32 v78, 1, v78
	v_max_u32_e32 v66, 1, v66
	v_lshl_or_b32 v66, v66, 8, v78
	v_max_u32_sdwa v67, v67, v175 dst_sel:WORD_1 dst_unused:UNUSED_PAD src0_sel:DWORD src1_sel:DWORD
	v_max_u32_sdwa v68, v68, v175 dst_sel:BYTE_3 dst_unused:UNUSED_PAD src0_sel:DWORD src1_sel:DWORD
	v_add_f32_e32 v77, 1.0, v77
	v_or3_b32 v66, v66, v67, v68
	v_fma_f32 v67, v74, s80, 0.5
	v_fma_f32 v68, v75, s80, 0.5
	v_cvt_u32_f32_e32 v67, v67
	v_cvt_u32_f32_e32 v68, v68
	v_fma_f32 v74, v76, s80, 0.5
	v_add_f32_e32 v70, 1.0, v70
	v_add_f32_e32 v71, 1.0, v71
	v_fma_f32 v72, v72, v99, v88
	v_fmac_f32_e32 v89, v73, v99
	v_rcp_f32_e32 v77, v77
	v_cvt_u32_f32_e32 v74, v74
	v_rcp_f32_e32 v70, v70
	v_rcp_f32_e32 v71, v71
	v_mul_f32_e32 v72, 0xbfb8aa3b, v72
	v_mul_f32_e32 v73, 0xbfb8aa3b, v89
	v_exp_f32_e32 v72, v72
	v_exp_f32_e32 v73, v73
	v_max_u32_e32 v67, 1, v67
	v_max_u32_e32 v68, 1, v68
	v_lshl_or_b32 v67, v68, 8, v67
	v_max_u32_sdwa v68, v74, v175 dst_sel:WORD_1 dst_unused:UNUSED_PAD src0_sel:DWORD src1_sel:DWORD
	v_fma_f32 v74, v77, s80, 0.5
	v_cvt_u32_f32_e32 v74, v74
	v_fma_f32 v70, v70, s80, 0.5
	v_fma_f32 v71, v71, s80, 0.5
	v_add_f32_e32 v72, 1.0, v72
	v_add_f32_e32 v73, 1.0, v73
	v_cvt_u32_f32_e32 v70, v70
	v_cvt_u32_f32_e32 v71, v71
	v_rcp_f32_e32 v72, v72
	v_fmac_f32_e32 v85, v69, v99
	v_rcp_f32_e32 v73, v73
	v_mul_f32_e32 v69, 0xbfb8aa3b, v85
	v_exp_f32_e32 v69, v69
	v_max_u32_sdwa v74, v74, v175 dst_sel:BYTE_3 dst_unused:UNUSED_PAD src0_sel:DWORD src1_sel:DWORD
	v_add_f32_e32 v69, 1.0, v69
	v_or3_b32 v67, v67, v68, v74
	v_max_u32_e32 v68, 1, v70
	v_max_u32_e32 v70, 1, v71
	v_lshl_or_b32 v68, v70, 8, v68
	v_fma_f32 v70, v72, s80, 0.5
	v_fma_f32 v71, v73, s80, 0.5
	v_cvt_u32_f32_e32 v70, v70
	v_cvt_u32_f32_e32 v71, v71
	v_fma_f32 v72, v82, s80, 0.5
	v_rcp_f32_e32 v69, v69
	v_cvt_u32_f32_e32 v72, v72
	v_max_u32_sdwa v70, v70, v175 dst_sel:WORD_1 dst_unused:UNUSED_PAD src0_sel:DWORD src1_sel:DWORD
	v_max_u32_sdwa v71, v71, v175 dst_sel:BYTE_3 dst_unused:UNUSED_PAD src0_sel:DWORD src1_sel:DWORD
	v_fma_f32 v69, v69, s80, 0.5
	v_or3_b32 v68, v68, v70, v71
	v_fma_f32 v71, v80, s80, 0.5
	v_max_u32_e32 v70, 1, v72
	v_cvt_u32_f32_e32 v71, v71
	v_fma_f32 v72, v81, s80, 0.5
	v_cvt_u32_f32_e32 v72, v72
	v_cvt_u32_f32_e32 v69, v69
	v_max_u32_e32 v71, 1, v71
	v_lshl_or_b32 v70, v71, 8, v70
	v_max_u32_sdwa v71, v72, v175 dst_sel:WORD_1 dst_unused:UNUSED_PAD src0_sel:DWORD src1_sel:DWORD
	v_max_u32_sdwa v69, v69, v175 dst_sel:BYTE_3 dst_unused:UNUSED_PAD src0_sel:DWORD src1_sel:DWORD
	s_nop 0
	v_or3_b32 v69, v70, v71, v69
	v_mov_b32_e32 v70, v162
	s_nop 0
	v_ashrrev_i32_e32 v71, 31, v70
	v_lshl_add_u64 v[70:71], v[70:71], 4, s[22:23]
	v_add_co_u32_e32 v70, vcc, s7, v70
	s_nop 1
	v_addc_co_u32_e32 v71, vcc, 0, v71, vcc
	global_store_dwordx4 v[70:71], v[66:69], off
	s_nop 0
	ds_read_b32 v82, v148
	s_mov_b32 s7, 0x13808000
	s_waitcnt vmcnt(4) lgkmcnt(0)
; DI float sigm(float x) { return frcp(1.f + fexp2(-kLog2e * x)); }
; DI unsigned q8fx4(float a, float b, float c, float d) { return q8f(a) | (q8f(b) << 8) | (q8f(c) << 16) | (q8f(d) << 24); }
; DI u32x4* gate_slot(const Params& P, int tile, int j, int g8) { return (u32x4*)slotp(P, SL_SK) + ((size_t)(tile * 3 + j) * 8 + g8) * 512 + tid(); }
; DI void gate_epilogue(const Params& P, int layer, int j, const f32x4 (&acc)[2][2][4][2], int tile, int n0, const char* lds) {
;     ...
;         const int col = n0 + ai * 128 + wr * 64 + 8 * fq;
;         const float* bg = P.b_gate + layer * 3072 + j * 1024 + col;
;         const f32x4 b0 = *(const f32x4*)bg, b1 = *(const f32x4*)(bg + 4), b2 = *(const f32x4*)(bg + 32), b3 = *(const f32x4*)(bg + 36);
; #pragma unroll
;         for (int bj = 0; bj < 2; ++bj)
; #pragma unroll
;             for (int nn = 0; nn < 2; ++nn) {
;                 const int rl = bj * 128 + wc * 32 + nn * 16 + fr;
;                 float lo[8], hi[8];
;                 grp16(acc, ai, bj, nn, rsl[rl], lo, hi);
; #pragma unroll
;                 for (int i = 0; i < 4; ++i) { lo[i] = sigm(lo[i] + b0[i]); lo[4 + i] = sigm(lo[4 + i] + b1[i]); hi[i] = sigm(hi[i] + b2[i]); hi[4 + i] = sigm(hi[4 + i] + b3[i]); }
;                 u32x4 o = {q8fx4(lo[0], lo[1], lo[2], lo[3]), q8fx4(lo[4], lo[5], lo[6], lo[7]), q8fx4(hi[0], hi[1], hi[2], hi[3]), q8fx4(hi[4], hi[5], hi[6], hi[7])};
;                 *gate_slot(P, tile, j, ai * 4 + bj * 2 + nn) = o;
	s_nop 1
	v_mov_b64_e32 v[78:79], v[200:201]
	v_mov_b64_e32 v[80:81], v[202:203]
	v_mov_b64_e32 v[74:75], v[204:205]
	v_mov_b64_e32 v[76:77], v[206:207]
	v_mov_b64_e32 v[70:71], v[208:209]
	v_mov_b64_e32 v[72:73], v[210:211]
	v_mov_b64_e32 v[66:67], v[212:213]
	v_mov_b64_e32 v[68:69], v[214:215]
	v_fma_f32 v62, v62, v82, v78
	v_fma_f32 v63, v63, v82, v79
	v_fma_f32 v64, v64, v82, v80
	v_fma_f32 v50, v50, v82, v66
	v_fma_f32 v51, v51, v82, v67
	v_fma_f32 v52, v52, v82, v68
	v_fma_f32 v65, v65, v82, v81
	v_mul_f32_e32 v62, 0xbfb8aa3b, v62
	v_mul_f32_e32 v50, 0xbfb8aa3b, v50
	v_mul_f32_e32 v63, 0xbfb8aa3b, v63
	v_mul_f32_e32 v51, 0xbfb8aa3b, v51
	v_mul_f32_e32 v64, 0xbfb8aa3b, v64
	v_mul_f32_e32 v52, 0xbfb8aa3b, v52
	v_mul_f32_e32 v65, 0xbfb8aa3b, v65
	v_exp_f32_e32 v62, v62
	v_exp_f32_e32 v50, v50
	v_exp_f32_e32 v63, v63
	v_exp_f32_e32 v51, v51
	v_exp_f32_e32 v64, v64
	v_exp_f32_e32 v52, v52
	v_exp_f32_e32 v65, v65
	v_add_f32_e32 v62, 1.0, v62
	v_add_f32_e32 v50, 1.0, v50
	v_add_f32_e32 v63, 1.0, v63
	v_fma_f32 v58, v58, v82, v74
	v_fma_f32 v54, v54, v82, v70
	v_fma_f32 v59, v59, v82, v75
	v_fma_f32 v55, v55, v82, v71
	v_fma_f32 v60, v60, v82, v76
	v_fma_f32 v56, v56, v82, v72
	v_fma_f32 v61, v61, v82, v77
	v_fma_f32 v57, v57, v82, v73
	v_fma_f32 v53, v53, v82, v69
	v_add_f32_e32 v51, 1.0, v51
	v_add_f32_e32 v64, 1.0, v64
	v_add_f32_e32 v52, 1.0, v52
	v_add_f32_e32 v65, 1.0, v65
	v_rcp_f32_e32 v62, v62
	v_rcp_f32_e32 v82, v50
	v_rcp_f32_e32 v50, v63
	v_mul_f32_e32 v58, 0xbfb8aa3b, v58
	v_mul_f32_e32 v59, 0xbfb8aa3b, v59
	v_rcp_f32_e32 v63, v51
	v_rcp_f32_e32 v51, v64
	v_rcp_f32_e32 v64, v52
	v_rcp_f32_e32 v52, v65
	v_mul_f32_e32 v60, 0xbfb8aa3b, v60
	v_exp_f32_e32 v58, v58
	v_exp_f32_e32 v59, v59
	v_exp_f32_e32 v60, v60
	v_fma_f32 v62, v62, s80, 0.5
	v_fma_f32 v50, v50, s80, 0.5
	v_fma_f32 v51, v51, s80, 0.5
	v_fma_f32 v52, v52, s80, 0.5
	v_cvt_u32_f32_e32 v62, v62
	v_cvt_u32_f32_e32 v50, v50
	v_add_f32_e32 v58, 1.0, v58
	v_add_f32_e32 v59, 1.0, v59
	v_cvt_u32_f32_e32 v51, v51
	v_cvt_u32_f32_e32 v52, v52
	v_mul_f32_e32 v61, 0xbfb8aa3b, v61
	v_add_f32_e32 v60, 1.0, v60
	v_rcp_f32_e32 v58, v58
	v_rcp_f32_e32 v59, v59
	v_mul_f32_e32 v54, 0xbfb8aa3b, v54
	v_mul_f32_e32 v55, 0xbfb8aa3b, v55
	v_exp_f32_e32 v61, v61
	v_rcp_f32_e32 v60, v60
	v_exp_f32_e32 v54, v54
	v_exp_f32_e32 v55, v55
	v_max_u32_e32 v62, 1, v62
	v_max_u32_e32 v50, 1, v50
	v_max_u32_sdwa v51, v51, v175 dst_sel:WORD_1 dst_unused:UNUSED_PAD src0_sel:DWORD src1_sel:DWORD
	v_max_u32_sdwa v52, v52, v175 dst_sel:BYTE_3 dst_unused:UNUSED_PAD src0_sel:DWORD src1_sel:DWORD
	v_lshl_or_b32 v50, v50, 8, v62
	v_or3_b32 v50, v50, v51, v52
	v_fma_f32 v51, v58, s80, 0.5
	v_fma_f32 v52, v59, s80, 0.5
	v_add_f32_e32 v61, 1.0, v61
	v_cvt_u32_f32_e32 v51, v51
	v_cvt_u32_f32_e32 v52, v52
	v_fma_f32 v58, v60, s80, 0.5
	v_add_f32_e32 v54, 1.0, v54
	v_add_f32_e32 v55, 1.0, v55
	v_rcp_f32_e32 v61, v61
	v_cvt_u32_f32_e32 v58, v58
	v_mul_f32_e32 v56, 0xbfb8aa3b, v56
	v_mul_f32_e32 v57, 0xbfb8aa3b, v57
	v_rcp_f32_e32 v54, v54
	v_rcp_f32_e32 v55, v55
	v_exp_f32_e32 v56, v56
	v_exp_f32_e32 v57, v57
	v_max_u32_e32 v51, 1, v51
	v_max_u32_e32 v52, 1, v52
	v_lshl_or_b32 v51, v52, 8, v51
	v_max_u32_sdwa v52, v58, v175 dst_sel:WORD_1 dst_unused:UNUSED_PAD src0_sel:DWORD src1_sel:DWORD
	v_fma_f32 v58, v61, s80, 0.5
	v_cvt_u32_f32_e32 v58, v58
	v_fma_f32 v54, v54, s80, 0.5
	v_fma_f32 v55, v55, s80, 0.5
	v_add_f32_e32 v56, 1.0, v56
	v_add_f32_e32 v57, 1.0, v57
	v_cvt_u32_f32_e32 v54, v54
	v_cvt_u32_f32_e32 v55, v55
	v_rcp_f32_e32 v56, v56
	v_rcp_f32_e32 v57, v57
	v_mul_f32_e32 v53, 0xbfb8aa3b, v53
	v_exp_f32_e32 v53, v53
	v_max_u32_sdwa v58, v58, v175 dst_sel:BYTE_3 dst_unused:UNUSED_PAD src0_sel:DWORD src1_sel:DWORD
	v_add_f32_e32 v53, 1.0, v53
	v_or3_b32 v51, v51, v52, v58
	v_max_u32_e32 v52, 1, v54
	v_max_u32_e32 v54, 1, v55
	v_lshl_or_b32 v52, v54, 8, v52
	v_fma_f32 v54, v56, s80, 0.5
	v_fma_f32 v55, v57, s80, 0.5
	v_cvt_u32_f32_e32 v54, v54
	v_cvt_u32_f32_e32 v55, v55
	v_fma_f32 v56, v82, s80, 0.5
	v_rcp_f32_e32 v53, v53
	v_cvt_u32_f32_e32 v56, v56
	v_max_u32_sdwa v54, v54, v175 dst_sel:WORD_1 dst_unused:UNUSED_PAD src0_sel:DWORD src1_sel:DWORD
	v_max_u32_sdwa v55, v55, v175 dst_sel:BYTE_3 dst_unused:UNUSED_PAD src0_sel:DWORD src1_sel:DWORD
	v_fma_f32 v53, v53, s80, 0.5
	v_or3_b32 v52, v52, v54, v55
	v_fma_f32 v55, v63, s80, 0.5
	v_max_u32_e32 v54, 1, v56
	v_cvt_u32_f32_e32 v55, v55
	v_fma_f32 v56, v64, s80, 0.5
	v_cvt_u32_f32_e32 v56, v56
	v_cvt_u32_f32_e32 v53, v53
	v_max_u32_e32 v55, 1, v55
	v_lshl_or_b32 v54, v55, 8, v54
	v_max_u32_sdwa v55, v56, v175 dst_sel:WORD_1 dst_unused:UNUSED_PAD src0_sel:DWORD src1_sel:DWORD
	v_max_u32_sdwa v53, v53, v175 dst_sel:BYTE_3 dst_unused:UNUSED_PAD src0_sel:DWORD src1_sel:DWORD
	s_nop 0
	v_or3_b32 v53, v54, v55, v53
	v_mov_b32_e32 v54, v162
	s_nop 0
	v_ashrrev_i32_e32 v55, 31, v54
	v_lshl_add_u64 v[54:55], v[54:55], 4, s[22:23]
	v_add_co_u32_e32 v54, vcc, s7, v54
	s_nop 1
	v_addc_co_u32_e32 v55, vcc, 0, v55, vcc
	global_store_dwordx4 v[54:55], v[50:53], off
	ds_read_b32 v0, v0
	s_mov_b32 s7, 0x1380a000
	s_waitcnt lgkmcnt(0)
; DI float sigm(float x) { return frcp(1.f + fexp2(-kLog2e * x)); }
; DI unsigned q8fx4(float a, float b, float c, float d) { return q8f(a) | (q8f(b) << 8) | (q8f(c) << 16) | (q8f(d) << 24); }
; DI u32x4* gate_slot(const Params& P, int tile, int j, int g8) { return (u32x4*)slotp(P, SL_SK) + ((size_t)(tile * 3 + j) * 8 + g8) * 512 + tid(); }
; DI void gate_epilogue(const Params& P, int layer, int j, const f32x4 (&acc)[2][2][4][2], int tile, int n0, const char* lds) {
;     ...
;                 const int rl = bj * 128 + wc * 32 + nn * 16 + fr;
;                 float lo[8], hi[8];
;                 grp16(acc, ai, bj, nn, rsl[rl], lo, hi);
; #pragma unroll
;                 for (int i = 0; i < 4; ++i) { lo[i] = sigm(lo[i] + b0[i]); lo[4 + i] = sigm(lo[4 + i] + b1[i]); hi[i] = sigm(hi[i] + b2[i]); hi[4 + i] = sigm(hi[4 + i] + b3[i]); }
;                 u32x4 o = {q8fx4(lo[0], lo[1], lo[2], lo[3]), q8fx4(lo[4], lo[5], lo[6], lo[7]), q8fx4(hi[0], hi[1], hi[2], hi[3]), q8fx4(hi[4], hi[5], hi[6], hi[7])};
;                 *gate_slot(P, tile, j, ai * 4 + bj * 2 + nn) = o;
	v_fma_f32 v34, v34, v0, v66
	v_mul_f32_e32 v34, 0xbfb8aa3b, v34
	v_fma_f32 v47, v47, v0, v79
	v_exp_f32_e32 v34, v34
	v_mul_f32_e32 v47, 0xbfb8aa3b, v47
	v_exp_f32_e32 v47, v47
	v_fma_f32 v35, v35, v0, v67
	v_add_f32_e32 v34, 1.0, v34
	v_rcp_f32_e32 v50, v34
	v_add_f32_e32 v34, 1.0, v47
	v_mul_f32_e32 v35, 0xbfb8aa3b, v35
	v_fma_f32 v47, v48, v0, v80
	v_exp_f32_e32 v35, v35
	v_mul_f32_e32 v47, 0xbfb8aa3b, v47
	v_exp_f32_e32 v47, v47
	v_fma_f32 v46, v46, v0, v78
	v_add_f32_e32 v35, 1.0, v35
	v_fma_f32 v36, v36, v0, v68
	v_mul_f32_e32 v46, 0xbfb8aa3b, v46
	v_rcp_f32_e32 v48, v35
	v_add_f32_e32 v35, 1.0, v47
	v_mul_f32_e32 v36, 0xbfb8aa3b, v36
	v_fma_f32 v47, v49, v0, v81
	v_exp_f32_e32 v46, v46
	v_exp_f32_e32 v36, v36
	v_mul_f32_e32 v47, 0xbfb8aa3b, v47
	v_exp_f32_e32 v47, v47
	v_add_f32_e32 v46, 1.0, v46
	v_add_f32_e32 v36, 1.0, v36
	v_fma_f32 v42, v42, v0, v74
	v_rcp_f32_e32 v46, v46
	v_fma_f32 v43, v43, v0, v75
	v_rcp_f32_e32 v34, v34
	v_rcp_f32_e32 v49, v36
	v_add_f32_e32 v36, 1.0, v47
	v_mul_f32_e32 v42, 0xbfb8aa3b, v42
	v_mul_f32_e32 v43, 0xbfb8aa3b, v43
	v_fma_f32 v44, v44, v0, v76
	v_rcp_f32_e32 v35, v35
	v_rcp_f32_e32 v36, v36
	v_exp_f32_e32 v42, v42
	v_exp_f32_e32 v43, v43
	v_mul_f32_e32 v44, 0xbfb8aa3b, v44
	v_exp_f32_e32 v44, v44
	v_fma_f32 v38, v38, v0, v70
	v_fma_f32 v39, v39, v0, v71
	v_fma_f32 v40, v40, v0, v72
	v_fma_f32 v45, v45, v0, v77
	v_fma_f32 v41, v41, v0, v73
	v_fma_f32 v0, v37, v0, v69
	v_fma_f32 v37, v46, s80, 0.5
	v_fma_f32 v34, v34, s80, 0.5
	v_cvt_u32_f32_e32 v37, v37
	v_cvt_u32_f32_e32 v34, v34
	v_fma_f32 v35, v35, s80, 0.5
	v_fma_f32 v36, v36, s80, 0.5
	v_add_f32_e32 v42, 1.0, v42
	v_add_f32_e32 v43, 1.0, v43
	v_cvt_u32_f32_e32 v35, v35
	v_cvt_u32_f32_e32 v36, v36
	v_rcp_f32_e32 v42, v42
	v_rcp_f32_e32 v43, v43
	v_add_f32_e32 v44, 1.0, v44
	v_mul_f32_e32 v45, 0xbfb8aa3b, v45
	v_mul_f32_e32 v38, 0xbfb8aa3b, v38
	v_mul_f32_e32 v39, 0xbfb8aa3b, v39
	v_rcp_f32_e32 v44, v44
	v_exp_f32_e32 v45, v45
	v_exp_f32_e32 v38, v38
	v_exp_f32_e32 v39, v39
	v_max_u32_e32 v37, 1, v37
	v_max_u32_e32 v34, 1, v34
	v_lshl_or_b32 v34, v34, 8, v37
	v_max_u32_sdwa v35, v35, v175 dst_sel:WORD_1 dst_unused:UNUSED_PAD src0_sel:DWORD src1_sel:DWORD
	v_max_u32_sdwa v36, v36, v175 dst_sel:BYTE_3 dst_unused:UNUSED_PAD src0_sel:DWORD src1_sel:DWORD
	v_add_f32_e32 v45, 1.0, v45
	v_or3_b32 v34, v34, v35, v36
	v_fma_f32 v35, v42, s80, 0.5
	v_fma_f32 v36, v43, s80, 0.5
	v_cvt_u32_f32_e32 v35, v35
	v_cvt_u32_f32_e32 v36, v36
	v_fma_f32 v37, v44, s80, 0.5
	v_add_f32_e32 v38, 1.0, v38
	v_add_f32_e32 v39, 1.0, v39
	v_rcp_f32_e32 v45, v45
	v_cvt_u32_f32_e32 v37, v37
	v_rcp_f32_e32 v38, v38
	v_rcp_f32_e32 v39, v39
	v_mul_f32_e32 v40, 0xbfb8aa3b, v40
	v_mul_f32_e32 v41, 0xbfb8aa3b, v41
	v_exp_f32_e32 v40, v40
	v_exp_f32_e32 v41, v41
	v_max_u32_e32 v35, 1, v35
	v_max_u32_e32 v36, 1, v36
	v_lshl_or_b32 v35, v36, 8, v35
	v_max_u32_sdwa v36, v37, v175 dst_sel:WORD_1 dst_unused:UNUSED_PAD src0_sel:DWORD src1_sel:DWORD
	v_fma_f32 v37, v45, s80, 0.5
	v_cvt_u32_f32_e32 v37, v37
	v_fma_f32 v38, v38, s80, 0.5
	v_fma_f32 v39, v39, s80, 0.5
	v_add_f32_e32 v40, 1.0, v40
	v_add_f32_e32 v41, 1.0, v41
	v_cvt_u32_f32_e32 v38, v38
	v_cvt_u32_f32_e32 v39, v39
	v_rcp_f32_e32 v40, v40
	v_rcp_f32_e32 v41, v41
	v_mul_f32_e32 v0, 0xbfb8aa3b, v0
	v_exp_f32_e32 v0, v0
	v_max_u32_sdwa v37, v37, v175 dst_sel:BYTE_3 dst_unused:UNUSED_PAD src0_sel:DWORD src1_sel:DWORD
	v_add_f32_e32 v0, 1.0, v0
	v_or3_b32 v35, v35, v36, v37
	v_max_u32_e32 v36, 1, v38
	v_max_u32_e32 v37, 1, v39
	v_lshl_or_b32 v36, v37, 8, v36
	v_fma_f32 v37, v40, s80, 0.5
	v_fma_f32 v38, v41, s80, 0.5
	v_cvt_u32_f32_e32 v37, v37
	v_cvt_u32_f32_e32 v38, v38
	v_fma_f32 v39, v50, s80, 0.5
	v_rcp_f32_e32 v0, v0
	v_cvt_u32_f32_e32 v39, v39
	v_max_u32_sdwa v37, v37, v175 dst_sel:WORD_1 dst_unused:UNUSED_PAD src0_sel:DWORD src1_sel:DWORD
	v_max_u32_sdwa v38, v38, v175 dst_sel:BYTE_3 dst_unused:UNUSED_PAD src0_sel:DWORD src1_sel:DWORD
	v_fma_f32 v0, v0, s80, 0.5
	v_or3_b32 v36, v36, v37, v38
	v_fma_f32 v38, v48, s80, 0.5
	v_max_u32_e32 v37, 1, v39
	v_cvt_u32_f32_e32 v38, v38
	v_fma_f32 v39, v49, s80, 0.5
	v_cvt_u32_f32_e32 v39, v39
	v_cvt_u32_f32_e32 v0, v0
	v_max_u32_e32 v38, 1, v38
	v_lshl_or_b32 v37, v38, 8, v37
	v_max_u32_sdwa v38, v39, v175 dst_sel:WORD_1 dst_unused:UNUSED_PAD src0_sel:DWORD src1_sel:DWORD
	v_max_u32_sdwa v0, v0, v175 dst_sel:BYTE_3 dst_unused:UNUSED_PAD src0_sel:DWORD src1_sel:DWORD
	s_nop 0
	v_or3_b32 v37, v37, v38, v0
	v_mov_b32_e32 v38, v162
	s_nop 0
	v_ashrrev_i32_e32 v39, 31, v38
	v_lshl_add_u64 v[38:39], v[38:39], 4, s[22:23]
	v_add_co_u32_e32 v38, vcc, s7, v38
	s_nop 1
	v_addc_co_u32_e32 v39, vcc, 0, v39, vcc
	global_store_dwordx4 v[38:39], v[34:37], off
	ds_read_b32 v0, v114
	s_mov_b32 s7, 0x1380c000
	s_waitcnt lgkmcnt(0)
; DI float sigm(float x) { return frcp(1.f + fexp2(-kLog2e * x)); }
; DI unsigned q8fx4(float a, float b, float c, float d) { return q8f(a) | (q8f(b) << 8) | (q8f(c) << 16) | (q8f(d) << 24); }
; DI u32x4* gate_slot(const Params& P, int tile, int j, int g8) { return (u32x4*)slotp(P, SL_SK) + ((size_t)(tile * 3 + j) * 8 + g8) * 512 + tid(); }
; DI void gate_epilogue(const Params& P, int layer, int j, const f32x4 (&acc)[2][2][4][2], int tile, int n0, const char* lds) {
;     ...
;                 const int rl = bj * 128 + wc * 32 + nn * 16 + fr;
;                 float lo[8], hi[8];
;                 grp16(acc, ai, bj, nn, rsl[rl], lo, hi);
; #pragma unroll
;                 for (int i = 0; i < 4; ++i) { lo[i] = sigm(lo[i] + b0[i]); lo[4 + i] = sigm(lo[4 + i] + b1[i]); hi[i] = sigm(hi[i] + b2[i]); hi[4 + i] = sigm(hi[4 + i] + b3[i]); }
;                 u32x4 o = {q8fx4(lo[0], lo[1], lo[2], lo[3]), q8fx4(lo[4], lo[5], lo[6], lo[7]), q8fx4(hi[0], hi[1], hi[2], hi[3]), q8fx4(hi[4], hi[5], hi[6], hi[7])};
;                 *gate_slot(P, tile, j, ai * 4 + bj * 2 + nn) = o;
	v_fma_f32 v18, v18, v0, v66
	v_mul_f32_e32 v18, 0xbfb8aa3b, v18
	v_fma_f32 v31, v31, v0, v79
	v_exp_f32_e32 v18, v18
	v_mul_f32_e32 v31, 0xbfb8aa3b, v31
	v_exp_f32_e32 v31, v31
	v_fma_f32 v19, v19, v0, v67
	v_add_f32_e32 v18, 1.0, v18
	v_rcp_f32_e32 v34, v18
	v_add_f32_e32 v18, 1.0, v31
	v_mul_f32_e32 v19, 0xbfb8aa3b, v19
	v_fma_f32 v31, v32, v0, v80
	v_exp_f32_e32 v19, v19
	v_mul_f32_e32 v31, 0xbfb8aa3b, v31
	v_exp_f32_e32 v31, v31
	v_fma_f32 v30, v30, v0, v78
	v_add_f32_e32 v19, 1.0, v19
	v_fma_f32 v20, v20, v0, v68
	v_mul_f32_e32 v30, 0xbfb8aa3b, v30
	v_rcp_f32_e32 v32, v19
	v_add_f32_e32 v19, 1.0, v31
	v_mul_f32_e32 v20, 0xbfb8aa3b, v20
	v_fma_f32 v31, v33, v0, v81
	v_exp_f32_e32 v30, v30
	v_exp_f32_e32 v20, v20
	v_mul_f32_e32 v31, 0xbfb8aa3b, v31
	v_exp_f32_e32 v31, v31
	v_add_f32_e32 v30, 1.0, v30
	v_add_f32_e32 v20, 1.0, v20
	v_fma_f32 v26, v26, v0, v74
	v_rcp_f32_e32 v30, v30
	v_fma_f32 v27, v27, v0, v75
	v_rcp_f32_e32 v18, v18
	v_rcp_f32_e32 v33, v20
	v_add_f32_e32 v20, 1.0, v31
	v_mul_f32_e32 v26, 0xbfb8aa3b, v26
	v_mul_f32_e32 v27, 0xbfb8aa3b, v27
	v_fma_f32 v28, v28, v0, v76
	v_rcp_f32_e32 v19, v19
	v_rcp_f32_e32 v20, v20
	v_exp_f32_e32 v26, v26
	v_exp_f32_e32 v27, v27
	v_mul_f32_e32 v28, 0xbfb8aa3b, v28
	v_exp_f32_e32 v28, v28
	v_fma_f32 v22, v22, v0, v70
	v_fma_f32 v23, v23, v0, v71
	v_fma_f32 v24, v24, v0, v72
	v_fma_f32 v29, v29, v0, v77
	v_fma_f32 v25, v25, v0, v73
	v_fma_f32 v0, v21, v0, v69
	v_fma_f32 v21, v30, s80, 0.5
	v_fma_f32 v18, v18, s80, 0.5
	v_cvt_u32_f32_e32 v21, v21
	v_cvt_u32_f32_e32 v18, v18
	v_fma_f32 v19, v19, s80, 0.5
	v_fma_f32 v20, v20, s80, 0.5
	v_add_f32_e32 v26, 1.0, v26
	v_add_f32_e32 v27, 1.0, v27
	v_cvt_u32_f32_e32 v19, v19
	v_cvt_u32_f32_e32 v20, v20
	v_rcp_f32_e32 v26, v26
	v_rcp_f32_e32 v27, v27
	v_add_f32_e32 v28, 1.0, v28
	v_mul_f32_e32 v29, 0xbfb8aa3b, v29
	v_mul_f32_e32 v22, 0xbfb8aa3b, v22
	v_mul_f32_e32 v23, 0xbfb8aa3b, v23
	v_rcp_f32_e32 v28, v28
	v_exp_f32_e32 v29, v29
	v_exp_f32_e32 v22, v22
	v_exp_f32_e32 v23, v23
	v_max_u32_e32 v21, 1, v21
	v_max_u32_e32 v18, 1, v18
	v_lshl_or_b32 v18, v18, 8, v21
	v_max_u32_sdwa v19, v19, v175 dst_sel:WORD_1 dst_unused:UNUSED_PAD src0_sel:DWORD src1_sel:DWORD
	v_max_u32_sdwa v20, v20, v175 dst_sel:BYTE_3 dst_unused:UNUSED_PAD src0_sel:DWORD src1_sel:DWORD
	v_add_f32_e32 v29, 1.0, v29
	v_or3_b32 v18, v18, v19, v20
	v_fma_f32 v19, v26, s80, 0.5
	v_fma_f32 v20, v27, s80, 0.5
	v_cvt_u32_f32_e32 v19, v19
	v_cvt_u32_f32_e32 v20, v20
	v_fma_f32 v21, v28, s80, 0.5
	v_add_f32_e32 v22, 1.0, v22
	v_add_f32_e32 v23, 1.0, v23
	v_rcp_f32_e32 v29, v29
	v_cvt_u32_f32_e32 v21, v21
	v_rcp_f32_e32 v22, v22
	v_rcp_f32_e32 v23, v23
	v_mul_f32_e32 v24, 0xbfb8aa3b, v24
	v_mul_f32_e32 v25, 0xbfb8aa3b, v25
	v_exp_f32_e32 v24, v24
	v_exp_f32_e32 v25, v25
	v_max_u32_e32 v19, 1, v19
	v_max_u32_e32 v20, 1, v20
	v_lshl_or_b32 v19, v20, 8, v19
	v_max_u32_sdwa v20, v21, v175 dst_sel:WORD_1 dst_unused:UNUSED_PAD src0_sel:DWORD src1_sel:DWORD
	v_fma_f32 v21, v29, s80, 0.5
	v_cvt_u32_f32_e32 v21, v21
	v_fma_f32 v22, v22, s80, 0.5
	v_fma_f32 v23, v23, s80, 0.5
	v_add_f32_e32 v24, 1.0, v24
	v_add_f32_e32 v25, 1.0, v25
	v_cvt_u32_f32_e32 v22, v22
	v_cvt_u32_f32_e32 v23, v23
	v_rcp_f32_e32 v24, v24
	v_rcp_f32_e32 v25, v25
	v_mul_f32_e32 v0, 0xbfb8aa3b, v0
	v_exp_f32_e32 v0, v0
	v_max_u32_sdwa v21, v21, v175 dst_sel:BYTE_3 dst_unused:UNUSED_PAD src0_sel:DWORD src1_sel:DWORD
	v_add_f32_e32 v0, 1.0, v0
	v_or3_b32 v19, v19, v20, v21
	v_max_u32_e32 v20, 1, v22
	v_max_u32_e32 v21, 1, v23
	v_lshl_or_b32 v20, v21, 8, v20
	v_fma_f32 v21, v24, s80, 0.5
	v_fma_f32 v22, v25, s80, 0.5
	v_cvt_u32_f32_e32 v21, v21
	v_cvt_u32_f32_e32 v22, v22
	v_fma_f32 v23, v34, s80, 0.5
	v_rcp_f32_e32 v0, v0
	v_cvt_u32_f32_e32 v23, v23
	v_max_u32_sdwa v21, v21, v175 dst_sel:WORD_1 dst_unused:UNUSED_PAD src0_sel:DWORD src1_sel:DWORD
	v_max_u32_sdwa v22, v22, v175 dst_sel:BYTE_3 dst_unused:UNUSED_PAD src0_sel:DWORD src1_sel:DWORD
	v_fma_f32 v0, v0, s80, 0.5
	v_or3_b32 v20, v20, v21, v22
	v_fma_f32 v22, v32, s80, 0.5
	v_max_u32_e32 v21, 1, v23
	v_cvt_u32_f32_e32 v22, v22
	v_fma_f32 v23, v33, s80, 0.5
	v_cvt_u32_f32_e32 v23, v23
	v_cvt_u32_f32_e32 v0, v0
	v_max_u32_e32 v22, 1, v22
	v_lshl_or_b32 v21, v22, 8, v21
	v_max_u32_sdwa v22, v23, v175 dst_sel:WORD_1 dst_unused:UNUSED_PAD src0_sel:DWORD src1_sel:DWORD
	v_max_u32_sdwa v0, v0, v175 dst_sel:BYTE_3 dst_unused:UNUSED_PAD src0_sel:DWORD src1_sel:DWORD
	s_nop 0
	v_or3_b32 v21, v21, v22, v0
	v_mov_b32_e32 v22, v162
	s_nop 0
	v_ashrrev_i32_e32 v23, 31, v22
	v_lshl_add_u64 v[22:23], v[22:23], 4, s[22:23]
	v_add_co_u32_e32 v22, vcc, s7, v22
	s_nop 1
	v_addc_co_u32_e32 v23, vcc, 0, v23, vcc
	global_store_dwordx4 v[22:23], v[18:21], off
	ds_read_b32 v0, v98
	s_waitcnt lgkmcnt(0)
; DI float sigm(float x) { return frcp(1.f + fexp2(-kLog2e * x)); }
; DI unsigned q8fx4(float a, float b, float c, float d) { return q8f(a) | (q8f(b) << 8) | (q8f(c) << 16) | (q8f(d) << 24); }
; DI u32x4* gate_slot(const Params& P, int tile, int j, int g8) { return (u32x4*)slotp(P, SL_SK) + ((size_t)(tile * 3 + j) * 8 + g8) * 512 + tid(); }
; DI void gate_epilogue(const Params& P, int layer, int j, const f32x4 (&acc)[2][2][4][2], int tile, int n0, const char* lds) {
;     ...
;                 const int rl = bj * 128 + wc * 32 + nn * 16 + fr;
;                 float lo[8], hi[8];
;                 grp16(acc, ai, bj, nn, rsl[rl], lo, hi);
; #pragma unroll
;                 for (int i = 0; i < 4; ++i) { lo[i] = sigm(lo[i] + b0[i]); lo[4 + i] = sigm(lo[4 + i] + b1[i]); hi[i] = sigm(hi[i] + b2[i]); hi[4 + i] = sigm(hi[4 + i] + b3[i]); }
;                 u32x4 o = {q8fx4(lo[0], lo[1], lo[2], lo[3]), q8fx4(lo[4], lo[5], lo[6], lo[7]), q8fx4(hi[0], hi[1], hi[2], hi[3]), q8fx4(hi[4], hi[5], hi[6], hi[7])};
;                 *gate_slot(P, tile, j, ai * 4 + bj * 2 + nn) = o;
; DI void merge_phase(const Params& P, int layer, char* lds) {
;     ...
;         for (int j = 0; j < 3; ++j) {
	v_fma_f32 v2, v2, v0, v66
	v_mul_f32_e32 v2, 0xbfb8aa3b, v2
	v_fma_f32 v15, v15, v0, v79
	v_exp_f32_e32 v2, v2
	v_mul_f32_e32 v15, 0xbfb8aa3b, v15
	v_exp_f32_e32 v15, v15
	v_fma_f32 v3, v3, v0, v67
	v_add_f32_e32 v2, 1.0, v2
	v_rcp_f32_e32 v18, v2
	v_add_f32_e32 v2, 1.0, v15
	v_mul_f32_e32 v3, 0xbfb8aa3b, v3
	v_fma_f32 v15, v16, v0, v80
	v_exp_f32_e32 v3, v3
	v_mul_f32_e32 v15, 0xbfb8aa3b, v15
	v_exp_f32_e32 v15, v15
	v_fma_f32 v14, v14, v0, v78
	v_fma_f32 v4, v4, v0, v68
	v_mul_f32_e32 v14, 0xbfb8aa3b, v14
	v_add_f32_e32 v3, 1.0, v3
	v_mul_f32_e32 v4, 0xbfb8aa3b, v4
	v_fmac_f32_e32 v81, v17, v0
	v_exp_f32_e32 v14, v14
	v_rcp_f32_e32 v16, v3
	v_add_f32_e32 v3, 1.0, v15
	v_exp_f32_e32 v4, v4
	v_mul_f32_e32 v15, 0xbfb8aa3b, v81
	v_exp_f32_e32 v15, v15
	v_add_f32_e32 v14, 1.0, v14
	v_add_f32_e32 v4, 1.0, v4
	v_fma_f32 v10, v10, v0, v74
	v_rcp_f32_e32 v14, v14
	v_fma_f32 v11, v11, v0, v75
	v_rcp_f32_e32 v2, v2
	v_rcp_f32_e32 v17, v4
	v_add_f32_e32 v4, 1.0, v15
	v_mul_f32_e32 v10, 0xbfb8aa3b, v10
	v_mul_f32_e32 v11, 0xbfb8aa3b, v11
	v_fma_f32 v12, v12, v0, v76
	v_rcp_f32_e32 v3, v3
	v_rcp_f32_e32 v4, v4
	v_exp_f32_e32 v10, v10
	v_exp_f32_e32 v11, v11
	v_mul_f32_e32 v12, 0xbfb8aa3b, v12
	v_exp_f32_e32 v12, v12
	v_fmac_f32_e32 v69, v5, v0
	v_fma_f32 v5, v14, s80, 0.5
	v_fma_f32 v2, v2, s80, 0.5
	v_cvt_u32_f32_e32 v5, v5
	v_cvt_u32_f32_e32 v2, v2
	v_fma_f32 v3, v3, s80, 0.5
	v_fma_f32 v4, v4, s80, 0.5
	v_add_f32_e32 v10, 1.0, v10
	v_add_f32_e32 v11, 1.0, v11
	v_fmac_f32_e32 v77, v13, v0
	v_cvt_u32_f32_e32 v3, v3
	v_cvt_u32_f32_e32 v4, v4
	v_fma_f32 v6, v6, v0, v70
	v_rcp_f32_e32 v10, v10
	v_fma_f32 v7, v7, v0, v71
	v_rcp_f32_e32 v11, v11
	v_add_f32_e32 v12, 1.0, v12
	v_mul_f32_e32 v13, 0xbfb8aa3b, v77
	v_mul_f32_e32 v6, 0xbfb8aa3b, v6
	v_mul_f32_e32 v7, 0xbfb8aa3b, v7
	v_rcp_f32_e32 v12, v12
	v_exp_f32_e32 v13, v13
	v_exp_f32_e32 v6, v6
	v_exp_f32_e32 v7, v7
	v_max_u32_e32 v5, 1, v5
	v_max_u32_e32 v2, 1, v2
	v_lshl_or_b32 v2, v2, 8, v5
	v_max_u32_sdwa v3, v3, v175 dst_sel:WORD_1 dst_unused:UNUSED_PAD src0_sel:DWORD src1_sel:DWORD
	v_max_u32_sdwa v4, v4, v175 dst_sel:BYTE_3 dst_unused:UNUSED_PAD src0_sel:DWORD src1_sel:DWORD
	v_add_f32_e32 v13, 1.0, v13
	v_or3_b32 v2, v2, v3, v4
	v_fma_f32 v3, v10, s80, 0.5
	v_fma_f32 v4, v11, s80, 0.5
	v_cvt_u32_f32_e32 v3, v3
	v_cvt_u32_f32_e32 v4, v4
	v_fma_f32 v5, v12, s80, 0.5
	v_add_f32_e32 v6, 1.0, v6
	v_add_f32_e32 v7, 1.0, v7
	v_fma_f32 v8, v8, v0, v72
	v_fmac_f32_e32 v73, v9, v0
	v_rcp_f32_e32 v13, v13
	v_cvt_u32_f32_e32 v5, v5
	v_rcp_f32_e32 v6, v6
	v_rcp_f32_e32 v7, v7
	v_mul_f32_e32 v8, 0xbfb8aa3b, v8
	v_mul_f32_e32 v9, 0xbfb8aa3b, v73
	v_exp_f32_e32 v8, v8
	v_exp_f32_e32 v9, v9
	v_max_u32_e32 v3, 1, v3
	v_max_u32_e32 v4, 1, v4
	v_lshl_or_b32 v3, v4, 8, v3
	v_max_u32_sdwa v4, v5, v175 dst_sel:WORD_1 dst_unused:UNUSED_PAD src0_sel:DWORD src1_sel:DWORD
	v_fma_f32 v5, v13, s80, 0.5
	v_cvt_u32_f32_e32 v5, v5
	v_fma_f32 v6, v6, s80, 0.5
	v_fma_f32 v7, v7, s80, 0.5
	v_add_f32_e32 v8, 1.0, v8
	v_add_f32_e32 v9, 1.0, v9
	v_cvt_u32_f32_e32 v6, v6
	v_cvt_u32_f32_e32 v7, v7
	v_rcp_f32_e32 v8, v8
	v_rcp_f32_e32 v9, v9
	v_mul_f32_e32 v0, 0xbfb8aa3b, v69
	v_exp_f32_e32 v0, v0
	v_max_u32_sdwa v5, v5, v175 dst_sel:BYTE_3 dst_unused:UNUSED_PAD src0_sel:DWORD src1_sel:DWORD
	v_add_f32_e32 v0, 1.0, v0
	v_or3_b32 v3, v3, v4, v5
	v_max_u32_e32 v4, 1, v6
	v_max_u32_e32 v5, 1, v7
	v_lshl_or_b32 v4, v5, 8, v4
	v_fma_f32 v5, v8, s80, 0.5
	v_fma_f32 v6, v9, s80, 0.5
	v_cvt_u32_f32_e32 v5, v5
	v_cvt_u32_f32_e32 v6, v6
	v_fma_f32 v7, v18, s80, 0.5
	v_rcp_f32_e32 v0, v0
	v_cvt_u32_f32_e32 v7, v7
	v_max_u32_sdwa v5, v5, v175 dst_sel:WORD_1 dst_unused:UNUSED_PAD src0_sel:DWORD src1_sel:DWORD
	v_max_u32_sdwa v6, v6, v175 dst_sel:BYTE_3 dst_unused:UNUSED_PAD src0_sel:DWORD src1_sel:DWORD
	v_fma_f32 v0, v0, s80, 0.5
	v_or3_b32 v4, v4, v5, v6
	v_fma_f32 v6, v16, s80, 0.5
	v_max_u32_e32 v5, 1, v7
	v_cvt_u32_f32_e32 v6, v6
	v_fma_f32 v7, v17, s80, 0.5
	v_cvt_u32_f32_e32 v7, v7
	v_cvt_u32_f32_e32 v0, v0
	v_max_u32_e32 v6, 1, v6
	v_lshl_or_b32 v5, v6, 8, v5
	v_max_u32_sdwa v6, v7, v175 dst_sel:WORD_1 dst_unused:UNUSED_PAD src0_sel:DWORD src1_sel:DWORD
	v_max_u32_sdwa v0, v0, v175 dst_sel:BYTE_3 dst_unused:UNUSED_PAD src0_sel:DWORD src1_sel:DWORD
	s_nop 0
	v_or3_b32 v5, v5, v6, v0
	v_mov_b32_e32 v6, v162
	s_nop 0
	v_ashrrev_i32_e32 v7, 31, v6
	v_lshl_add_u64 v[6:7], v[6:7], 4, s[22:23]
	v_add_co_u32_e32 v6, vcc, 0x1380e000, v6
	s_nop 1
	v_addc_co_u32_e32 v7, vcc, 0, v7, vcc
	global_store_dwordx4 v[6:7], v[2:5], off
	s_add_i32 s3, s3, 1
	s_addk_i32 s20, 0x400
	s_cmp_eq_u32 s3, 3
	s_cbranch_scc1 .LBB0_53
